# P0b h stores and P4 attn stores written through (sc1): less dirty L2 for the barrier release write-back
# baseline (speedup 1.0000x reference)
.LBB0_77:
	s_add_i32 s10, s2, s34
	s_cmpk_lt_i32 s10, 0x4000
	s_cselect_b32 s4, s10, s2
	s_ashr_i32 s3, s2, 31
	s_lshl_b64 s[6:7], s[2:3], 13
	v_lshl_add_u64 v[86:87], v[80:81], 0, s[6:7]
	global_load_dwordx4 v[76:79], v[86:87], off nt
	global_load_dwordx4 v[68:71], v[86:87], off offset:1024 nt
	global_load_dwordx4 v[72:75], v[86:87], off offset:2048 nt
	global_load_dwordx4 v[64:67], v[86:87], off offset:3072 nt
	s_ashr_i32 s5, s4, 31
	s_lshl_b64 s[6:7], s[4:5], 13
	v_add_co_u32_e32 v124, vcc, s1, v86
	v_lshl_add_u64 v[128:129], v[80:81], 0, s[6:7]
	s_nop 0
	v_addc_co_u32_e32 v125, vcc, 0, v87, vcc
	v_add_co_u32_e32 v140, vcc, s1, v128
	global_load_dwordx4 v[96:99], v[128:129], off nt
	global_load_dwordx4 v[100:103], v[128:129], off offset:1024 nt
	global_load_dwordx4 v[104:107], v[128:129], off offset:2048 nt
	global_load_dwordx4 v[108:111], v[124:125], off offset:1024 nt
	global_load_dwordx4 v[112:115], v[124:125], off nt
	global_load_dwordx4 v[116:119], v[128:129], off offset:3072 nt
	global_load_dwordx4 v[120:123], v[124:125], off offset:3072 nt
	s_nop 0
	global_load_dwordx4 v[124:127], v[124:125], off offset:2048 nt
	v_addc_co_u32_e32 v141, vcc, 0, v129, vcc
	global_load_dwordx4 v[128:131], v[140:141], off offset:1024 nt
	global_load_dwordx4 v[132:135], v[140:141], off nt
	global_load_dwordx4 v[136:139], v[140:141], off offset:3072 nt
	s_nop 0
	global_load_dwordx4 v[140:143], v[140:141], off offset:2048 nt
	s_lshl_b64 s[8:9], s[2:3], 12
	s_add_i32 s2, s10, s34
	s_lshl_b64 s[4:5], s[4:5], 12
	v_lshl_add_u64 v[84:85], v[82:83], 0, s[8:9]
	s_cmpk_gt_i32 s2, 0x3fff
	v_lshl_add_u64 v[86:87], v[82:83], 0, s[4:5]
	s_waitcnt vmcnt(15)
	v_mov_b32_e32 v146, v77
	s_waitcnt vmcnt(14)
	v_mov_b32_e32 v147, v69
	v_mov_b32_e32 v150, v79
	v_mov_b32_e32 v151, v71
	s_waitcnt vmcnt(13)
	v_pk_mul_f32 v[152:153], v[74:75], v[74:75]
	v_pk_mul_f32 v[154:155], v[72:73], v[72:73]
	v_mov_b32_e32 v144, v76
	v_mov_b32_e32 v145, v68
	v_mov_b32_e32 v148, v78
	v_mov_b32_e32 v149, v70
	v_pk_mul_f32 v[146:147], v[146:147], v[146:147]
	v_pk_mul_f32 v[150:151], v[150:151], v[150:151]
	v_pk_mov_b32 v[162:163], v[154:155], v[152:153] op_sel:[1,0]
	v_mov_b32_e32 v155, v153
	s_waitcnt vmcnt(11)
	v_mov_b32_e32 v170, v97
	s_waitcnt vmcnt(10)
	v_mov_b32_e32 v171, v101
	v_mov_b32_e32 v174, v99
	v_mov_b32_e32 v175, v103
	v_mov_b32_e32 v160, v96
	v_mov_b32_e32 v161, v100
	s_waitcnt vmcnt(9)
	v_pk_mul_f32 v[152:153], v[106:107], v[106:107]
	v_pk_mul_f32 v[164:165], v[104:105], v[104:105]
	v_mov_b32_e32 v172, v98
	v_mov_b32_e32 v173, v102
	v_pk_fma_f32 v[144:145], v[144:145], v[144:145], v[146:147]
	v_pk_fma_f32 v[146:147], v[148:149], v[148:149], v[150:151]
	v_pk_add_f32 v[148:149], v[162:163], v[154:155]
	v_pk_mul_f32 v[154:155], v[170:171], v[170:171]
	v_pk_mul_f32 v[162:163], v[174:175], v[174:175]
	v_mul_f32_e32 v156, v65, v65
	v_mul_f32_e32 v158, v67, v67
	v_pk_mov_b32 v[150:151], v[164:165], v[152:153] op_sel:[1,0]
	v_mov_b32_e32 v165, v153
	v_pk_add_f32 v[144:145], v[144:145], v[146:147]
	v_pk_fma_f32 v[146:147], v[160:161], v[160:161], v[154:155]
	v_pk_fma_f32 v[154:155], v[172:173], v[172:173], v[162:163]
	s_waitcnt vmcnt(7)
	v_mul_f32_e32 v95, v114, v114
	v_pk_fma_f32 v[156:157], v[64:65], v[64:65], v[156:157] op_sel_hi:[1,1,0]
	v_mul_f32_e32 v177, v115, v115
	v_pk_fma_f32 v[158:159], v[66:67], v[66:67], v[158:159] op_sel_hi:[1,1,0]
	s_waitcnt vmcnt(6)
	v_mul_f32_e32 v176, v117, v117
	v_mul_f32_e32 v178, v119, v119
	v_mul_f32_e32 v186, v113, v113
	v_mul_f32_e32 v187, v112, v112
	v_pk_add_f32 v[150:151], v[150:151], v[164:165]
	v_pk_add_f32 v[148:149], v[148:149], v[148:149] op_sel:[0,1] op_sel_hi:[1,0]
	v_pk_add_f32 v[146:147], v[146:147], v[154:155]
	v_pk_add_f32 v[144:145], v[144:145], v[144:145] op_sel:[0,1] op_sel_hi:[1,0]
	v_pk_mul_f32 v[166:167], v[110:111], v[110:111]
	v_pk_mul_f32 v[168:169], v[108:109], v[108:109]
	v_mov_b32_e32 v157, v95
	v_mov_b32_e32 v159, v177
	s_waitcnt vmcnt(2)
	v_mul_f32_e32 v95, v134, v134
	v_pk_fma_f32 v[174:175], v[116:117], v[116:117], v[176:177] op_sel_hi:[1,1,0]
	v_mul_f32_e32 v190, v135, v135
	v_pk_fma_f32 v[176:177], v[118:119], v[118:119], v[178:179] op_sel_hi:[1,1,0]
	v_mul_f32_e32 v195, v133, v133
	v_mul_f32_e32 v196, v132, v132
	v_mov_b32_e32 v149, v186
	v_pk_add_f32 v[150:151], v[150:151], v[150:151] op_sel:[0,1] op_sel_hi:[1,0]
	v_mov_b32_e32 v145, v187
	v_pk_add_f32 v[146:147], v[146:147], v[146:147] op_sel:[0,1] op_sel_hi:[1,0]
	v_pk_mov_b32 v[152:153], v[168:169], v[166:167] op_sel:[1,0]
	v_mov_b32_e32 v169, v167
	v_pk_mul_f32 v[166:167], v[130:131], v[130:131]
	v_pk_mul_f32 v[170:171], v[128:129], v[128:129]
	v_pk_add_f32 v[156:157], v[156:157], v[158:159]
	v_mov_b32_e32 v175, v95
	v_mov_b32_e32 v177, v190
	v_mov_b32_e32 v151, v195
	v_pk_add_f32 v[144:145], v[144:145], v[148:149]
	v_mov_b32_e32 v147, v196
	v_mul_f32_e32 v183, v122, v122
	v_mul_f32_e32 v180, v125, v125
	v_mul_f32_e32 v182, v127, v127
	v_pk_add_f32 v[152:153], v[152:153], v[168:169]
	v_pk_mov_b32 v[158:159], v[170:171], v[166:167] op_sel:[1,0]
	v_mov_b32_e32 v171, v167
	v_pk_add_f32 v[154:155], v[174:175], v[176:177]
	v_pk_add_f32 v[144:145], v[144:145], v[156:157]
	v_pk_add_f32 v[146:147], v[146:147], v[150:151]
	v_mul_f32_e32 v185, v123, v123
	v_mul_f32_e32 v188, v120, v120
	v_mul_f32_e32 v189, v121, v121
	v_pk_fma_f32 v[178:179], v[124:125], v[124:125], v[180:181] op_sel_hi:[1,1,0]
	v_pk_fma_f32 v[180:181], v[126:127], v[126:127], v[182:183] op_sel_hi:[1,1,0]
	s_waitcnt vmcnt(0)
	v_mul_f32_e32 v182, v141, v141
	v_mul_f32_e32 v184, v143, v143
	v_pk_add_f32 v[158:159], v[158:159], v[170:171]
	v_pk_add_f32 v[152:153], v[152:153], v[152:153] op_sel:[0,1] op_sel_hi:[1,0]
	v_pk_add_f32 v[146:147], v[146:147], v[154:155]
	v_pk_add_f32 v[144:145], v[144:145], v[144:145] op_sel:[0,1] op_sel_hi:[1,0]
	v_mul_f32_e32 v191, v138, v138
	v_mul_f32_e32 v194, v139, v139
	v_mul_f32_e32 v197, v136, v136
	v_mul_f32_e32 v198, v137, v137
	v_mov_b32_e32 v179, v183
	v_mov_b32_e32 v181, v185
	v_pk_fma_f32 v[160:161], v[140:141], v[140:141], v[182:183] op_sel_hi:[1,1,0]
	v_pk_fma_f32 v[162:163], v[142:143], v[142:143], v[184:185] op_sel_hi:[1,1,0]
	v_mov_b32_e32 v153, v189
	v_pk_add_f32 v[158:159], v[158:159], v[158:159] op_sel:[0,1] op_sel_hi:[1,0]
	v_mov_b32_e32 v145, v188
	v_pk_add_f32 v[146:147], v[146:147], v[146:147] op_sel:[0,1] op_sel_hi:[1,0]
	v_pk_add_f32 v[164:165], v[178:179], v[180:181]
	v_mov_b32_e32 v161, v191
	v_mov_b32_e32 v163, v194
	v_mov_b32_e32 v159, v198
	v_pk_add_f32 v[144:145], v[144:145], v[152:153]
	v_mov_b32_e32 v147, v197
	v_pk_add_f32 v[160:161], v[160:161], v[162:163]
	v_pk_add_f32 v[144:145], v[144:145], v[164:165]
	v_pk_add_f32 v[146:147], v[146:147], v[158:159]
	v_add_f32_e32 v95, v144, v145
	v_pk_add_f32 v[144:145], v[146:147], v[160:161]
	ds_bpermute_b32 v146, v88, v95
	v_add_f32_e32 v144, v144, v145
	ds_bpermute_b32 v145, v88, v144
	s_waitcnt lgkmcnt(1)
	v_add_f32_e32 v95, v95, v146
	ds_bpermute_b32 v146, v89, v95
	s_waitcnt lgkmcnt(1)
	v_add_f32_e32 v144, v144, v145
	ds_bpermute_b32 v145, v89, v144
	s_waitcnt lgkmcnt(1)
	v_add_f32_e32 v95, v95, v146
	ds_bpermute_b32 v146, v90, v95
	s_waitcnt lgkmcnt(1)
	v_add_f32_e32 v144, v144, v145
	ds_bpermute_b32 v145, v90, v144
	s_waitcnt lgkmcnt(1)
	v_add_f32_e32 v95, v95, v146
	ds_bpermute_b32 v146, v91, v95
	s_waitcnt lgkmcnt(1)
	v_add_f32_e32 v144, v144, v145
	ds_bpermute_b32 v145, v91, v144
	s_waitcnt lgkmcnt(1)
	v_add_f32_e32 v95, v95, v146
	ds_bpermute_b32 v146, v92, v95
	s_waitcnt lgkmcnt(1)
	v_add_f32_e32 v144, v144, v145
	ds_bpermute_b32 v145, v92, v144
	s_waitcnt lgkmcnt(1)
	v_add_f32_e32 v95, v95, v146
	ds_bpermute_b32 v146, v93, v95
	s_waitcnt lgkmcnt(1)
	v_add_f32_e32 v144, v144, v145
	ds_bpermute_b32 v145, v93, v144
	s_waitcnt lgkmcnt(1)
	v_add_f32_e32 v95, v95, v146
	v_fmamk_f32 v95, v95, 0x3a000000, v94
	s_waitcnt lgkmcnt(0)
	v_add_f32_e32 v145, v144, v145
	v_rsq_f32_e32 v144, v95
	v_fmamk_f32 v95, v145, 0x3a000000, v94
	v_rsq_f32_e32 v146, v95
	v_pk_mul_f32 v[76:77], v[144:145], v[76:77] op_sel_hi:[0,1]
	v_pk_mul_f32 v[78:79], v[144:145], v[78:79] op_sel_hi:[0,1]
	v_pk_mul_f32 v[68:69], v[144:145], v[68:69] op_sel_hi:[0,1]
	v_pk_mul_f32 v[70:71], v[144:145], v[70:71] op_sel_hi:[0,1]
	v_pk_mul_f32 v[72:73], v[144:145], v[72:73] op_sel_hi:[0,1]
	v_pk_mul_f32 v[74:75], v[144:145], v[74:75] op_sel_hi:[0,1]
	v_pk_mul_f32 v[64:65], v[144:145], v[64:65] op_sel_hi:[0,1]
	v_pk_mul_f32 v[66:67], v[144:145], v[66:67] op_sel_hi:[0,1]
	v_pk_mul_f32 v[112:113], v[144:145], v[112:113] op_sel_hi:[0,1]
	v_pk_mul_f32 v[114:115], v[144:145], v[114:115] op_sel_hi:[0,1]
	v_pk_mul_f32 v[108:109], v[144:145], v[108:109] op_sel_hi:[0,1]
	v_pk_mul_f32 v[110:111], v[144:145], v[110:111] op_sel_hi:[0,1]
	v_pk_mul_f32 v[124:125], v[144:145], v[124:125] op_sel_hi:[0,1]
	v_pk_mul_f32 v[126:127], v[144:145], v[126:127] op_sel_hi:[0,1]
	v_pk_mul_f32 v[120:121], v[144:145], v[120:121] op_sel_hi:[0,1]
	v_pk_mul_f32 v[122:123], v[144:145], v[122:123] op_sel_hi:[0,1]
	v_pk_fma_f32 v[78:79], v[2:3], v[78:79], v[10:11]
	v_pk_fma_f32 v[76:77], v[0:1], v[76:77], v[8:9]
	v_pk_mul_f32 v[96:97], v[146:147], v[96:97] op_sel_hi:[0,1]
	v_pk_mul_f32 v[98:99], v[146:147], v[98:99] op_sel_hi:[0,1]
	v_pk_fma_f32 v[70:71], v[6:7], v[70:71], v[14:15]
	v_pk_fma_f32 v[68:69], v[4:5], v[68:69], v[12:13]
	v_pk_mul_f32 v[100:101], v[146:147], v[100:101] op_sel_hi:[0,1]
	v_pk_mul_f32 v[102:103], v[146:147], v[102:103] op_sel_hi:[0,1]
	v_pk_fma_f32 v[74:75], v[18:19], v[74:75], v[26:27]
	v_pk_fma_f32 v[72:73], v[16:17], v[72:73], v[24:25]
	v_pk_mul_f32 v[104:105], v[146:147], v[104:105] op_sel_hi:[0,1]
	v_pk_mul_f32 v[106:107], v[146:147], v[106:107] op_sel_hi:[0,1]
	v_pk_fma_f32 v[66:67], v[22:23], v[66:67], v[30:31]
	v_pk_fma_f32 v[64:65], v[20:21], v[64:65], v[28:29]
	v_pk_mul_f32 v[116:117], v[146:147], v[116:117] op_sel_hi:[0,1]
	v_pk_mul_f32 v[118:119], v[146:147], v[118:119] op_sel_hi:[0,1]
	v_pk_fma_f32 v[114:115], v[34:35], v[114:115], v[42:43]
	v_pk_fma_f32 v[112:113], v[32:33], v[112:113], v[40:41]
	v_pk_mul_f32 v[132:133], v[146:147], v[132:133] op_sel_hi:[0,1]
	v_pk_mul_f32 v[134:135], v[146:147], v[134:135] op_sel_hi:[0,1]
	v_pk_fma_f32 v[110:111], v[38:39], v[110:111], v[46:47]
	v_pk_fma_f32 v[108:109], v[36:37], v[108:109], v[44:45]
	v_pk_mul_f32 v[128:129], v[146:147], v[128:129] op_sel_hi:[0,1]
	v_pk_mul_f32 v[130:131], v[146:147], v[130:131] op_sel_hi:[0,1]
	v_pk_fma_f32 v[126:127], v[50:51], v[126:127], v[58:59]
	v_pk_fma_f32 v[124:125], v[48:49], v[124:125], v[56:57]
	v_pk_mul_f32 v[140:141], v[146:147], v[140:141] op_sel_hi:[0,1]
	v_pk_mul_f32 v[142:143], v[146:147], v[142:143] op_sel_hi:[0,1]
	v_pk_fma_f32 v[122:123], v[54:55], v[122:123], v[62:63]
	v_pk_fma_f32 v[120:121], v[52:53], v[120:121], v[60:61]
	v_pk_mul_f32 v[136:137], v[146:147], v[136:137] op_sel_hi:[0,1]
	v_pk_mul_f32 v[138:139], v[146:147], v[138:139] op_sel_hi:[0,1]
	v_pk_fma_f32 v[98:99], v[2:3], v[98:99], v[10:11]
	v_pk_fma_f32 v[96:97], v[0:1], v[96:97], v[8:9]
	v_cvt_pk_bf16_f32 v76, v76, v77
	v_cvt_pk_bf16_f32 v77, v78, v79
	v_pk_fma_f32 v[78:79], v[6:7], v[102:103], v[14:15]
	v_pk_fma_f32 v[100:101], v[4:5], v[100:101], v[12:13]
	v_cvt_pk_bf16_f32 v68, v68, v69
	v_cvt_pk_bf16_f32 v69, v70, v71
	v_pk_fma_f32 v[70:71], v[18:19], v[106:107], v[26:27]
	v_pk_fma_f32 v[102:103], v[16:17], v[104:105], v[24:25]
	v_cvt_pk_bf16_f32 v72, v72, v73
	v_cvt_pk_bf16_f32 v73, v74, v75
	v_pk_fma_f32 v[74:75], v[22:23], v[118:119], v[30:31]
	v_pk_fma_f32 v[104:105], v[20:21], v[116:117], v[28:29]
	v_cvt_pk_bf16_f32 v64, v64, v65
	v_cvt_pk_bf16_f32 v65, v66, v67
	v_pk_fma_f32 v[66:67], v[34:35], v[134:135], v[42:43]
	v_pk_fma_f32 v[106:107], v[32:33], v[132:133], v[40:41]
	v_cvt_pk_bf16_f32 v112, v112, v113
	v_cvt_pk_bf16_f32 v113, v114, v115
	v_pk_fma_f32 v[114:115], v[38:39], v[130:131], v[46:47]
	v_pk_fma_f32 v[116:117], v[36:37], v[128:129], v[44:45]
	v_cvt_pk_bf16_f32 v108, v108, v109
	v_cvt_pk_bf16_f32 v109, v110, v111
	v_pk_fma_f32 v[110:111], v[50:51], v[142:143], v[58:59]
	v_pk_fma_f32 v[118:119], v[48:49], v[140:141], v[56:57]
	v_cvt_pk_bf16_f32 v124, v124, v125
	v_cvt_pk_bf16_f32 v125, v126, v127
	v_pk_fma_f32 v[126:127], v[54:55], v[138:139], v[62:63]
	v_pk_fma_f32 v[128:129], v[52:53], v[136:137], v[60:61]
	v_cvt_pk_bf16_f32 v120, v120, v121
	v_cvt_pk_bf16_f32 v121, v122, v123
	v_cvt_pk_bf16_f32 v96, v96, v97
	v_cvt_pk_bf16_f32 v97, v98, v99
	global_store_dwordx2 v[84:85], v[76:77], off sc1
	v_cvt_pk_bf16_f32 v76, v100, v101
	v_cvt_pk_bf16_f32 v77, v78, v79
	global_store_dwordx2 v[84:85], v[68:69], off offset:512 sc1
	v_cvt_pk_bf16_f32 v68, v102, v103
	v_cvt_pk_bf16_f32 v69, v70, v71
	global_store_dwordx2 v[84:85], v[72:73], off offset:1024 sc1
	v_cvt_pk_bf16_f32 v70, v104, v105
	v_cvt_pk_bf16_f32 v71, v74, v75
	global_store_dwordx2 v[84:85], v[64:65], off offset:1536 sc1
	v_cvt_pk_bf16_f32 v64, v106, v107
	v_cvt_pk_bf16_f32 v65, v66, v67
	global_store_dwordx2 v[84:85], v[112:113], off offset:2048 sc1
	v_cvt_pk_bf16_f32 v66, v116, v117
	v_cvt_pk_bf16_f32 v67, v114, v115
	global_store_dwordx2 v[84:85], v[108:109], off offset:2560 sc1
	v_cvt_pk_bf16_f32 v72, v118, v119
	v_cvt_pk_bf16_f32 v73, v110, v111
	global_store_dwordx2 v[84:85], v[124:125], off offset:3072 sc1
	v_cvt_pk_bf16_f32 v74, v128, v129
	v_cvt_pk_bf16_f32 v75, v126, v127
	global_store_dwordx2 v[84:85], v[120:121], off offset:3584 sc1
	global_store_dwordx2 v[86:87], v[96:97], off sc1
	global_store_dwordx2 v[86:87], v[76:77], off offset:512 sc1
	global_store_dwordx2 v[86:87], v[68:69], off offset:1024 sc1
	global_store_dwordx2 v[86:87], v[70:71], off offset:1536 sc1
	global_store_dwordx2 v[86:87], v[64:65], off offset:2048 sc1
	global_store_dwordx2 v[86:87], v[66:67], off offset:2560 sc1
	global_store_dwordx2 v[86:87], v[72:73], off offset:3072 sc1
	global_store_dwordx2 v[86:87], v[74:75], off offset:3584 sc1
	s_cbranch_scc0 .LBB0_77

.Lc4_outer:
	v_mov_b32_e32 v52, v20
	s_mov_b32 s12, s11
	v_cmp_gt_i32_e64 s[14:15], s10, v52
	v_mov_b32_e32 v55, 0
	s_nop 0
	v_cndmask_b32_e64 v52, v20, v52, s[14:15]
	v_ashrrev_i32_e32 v54, 7, v52
	v_ashrrev_i32_e32 v56, 15, v52
	v_lshlrev_b64 v[160:161], 13, v[54:55]
	v_lshlrev_b64 v[164:165], 7, v[54:55]
	v_lshl_add_u64 v[160:161], v[2:3], 0, v[160:161]
	v_lshl_add_u64 v[164:165], v[4:5], 0, v[164:165]
	v_lshl_add_u64 v[162:163], v[160:161], 0, s[6:7]
	global_load_dwordx4 v[32:35], v[160:161], off nt
	global_load_dword v48, v[164:165], off
	global_load_dwordx4 v[36:39], v[160:161], off offset:2048 nt
	global_load_dword v49, v[164:165], off offset:32
	global_load_dwordx4 v[40:43], v[162:163], off nt
	global_load_dword v50, v[164:165], off offset:64
	global_load_dwordx4 v[44:47], v[162:163], off offset:2048 nt
	global_load_dword v51, v[164:165], off offset:96
	v_add_u32_e32 v84, s12, v20
	s_add_i32 s12, s12, s11
	v_cmp_gt_i32_e64 s[16:17], s10, v84
	v_mov_b32_e32 v87, 0
	s_nop 0
	v_cndmask_b32_e64 v84, v20, v84, s[16:17]
	v_ashrrev_i32_e32 v86, 7, v84
	v_ashrrev_i32_e32 v88, 15, v84
	v_lshlrev_b64 v[160:161], 13, v[86:87]
	v_lshlrev_b64 v[164:165], 7, v[86:87]
	v_lshl_add_u64 v[160:161], v[2:3], 0, v[160:161]
	v_lshl_add_u64 v[164:165], v[4:5], 0, v[164:165]
	v_lshl_add_u64 v[162:163], v[160:161], 0, s[6:7]
	global_load_dwordx4 v[64:67], v[160:161], off nt
	global_load_dword v80, v[164:165], off
	global_load_dwordx4 v[68:71], v[160:161], off offset:2048 nt
	global_load_dword v81, v[164:165], off offset:32
	global_load_dwordx4 v[72:75], v[162:163], off nt
	global_load_dword v82, v[164:165], off offset:64
	global_load_dwordx4 v[76:79], v[162:163], off offset:2048 nt
	global_load_dword v83, v[164:165], off offset:96
	v_add_u32_e32 v116, s12, v20
	s_add_i32 s12, s12, s11
	v_cmp_gt_i32_e64 s[18:19], s10, v116
	v_mov_b32_e32 v119, 0
	s_nop 0
	v_cndmask_b32_e64 v116, v20, v116, s[18:19]
	v_ashrrev_i32_e32 v118, 7, v116
	v_ashrrev_i32_e32 v120, 15, v116
	v_lshlrev_b64 v[160:161], 13, v[118:119]
	v_lshlrev_b64 v[164:165], 7, v[118:119]
	v_lshl_add_u64 v[160:161], v[2:3], 0, v[160:161]
	v_lshl_add_u64 v[164:165], v[4:5], 0, v[164:165]
	v_lshl_add_u64 v[162:163], v[160:161], 0, s[6:7]
	global_load_dwordx4 v[96:99], v[160:161], off nt
	global_load_dword v112, v[164:165], off
	global_load_dwordx4 v[100:103], v[160:161], off offset:2048 nt
	global_load_dword v113, v[164:165], off offset:32
	global_load_dwordx4 v[104:107], v[162:163], off nt
	global_load_dword v114, v[164:165], off offset:64
	global_load_dwordx4 v[108:111], v[162:163], off offset:2048 nt
	global_load_dword v115, v[164:165], off offset:96
	v_add_u32_e32 v148, s12, v20
	v_cmp_gt_i32_e64 s[20:21], s10, v148
	v_mov_b32_e32 v151, 0
	s_nop 0
	v_cndmask_b32_e64 v148, v20, v148, s[20:21]
	v_ashrrev_i32_e32 v150, 7, v148
	v_ashrrev_i32_e32 v152, 15, v148
	v_lshlrev_b64 v[160:161], 13, v[150:151]
	v_lshlrev_b64 v[164:165], 7, v[150:151]
	v_lshl_add_u64 v[160:161], v[2:3], 0, v[160:161]
	v_lshl_add_u64 v[164:165], v[4:5], 0, v[164:165]
	v_lshl_add_u64 v[162:163], v[160:161], 0, s[6:7]
	global_load_dwordx4 v[128:131], v[160:161], off nt
	global_load_dword v144, v[164:165], off
	global_load_dwordx4 v[132:135], v[160:161], off offset:2048 nt
	global_load_dword v145, v[164:165], off offset:32
	global_load_dwordx4 v[136:139], v[162:163], off nt
	global_load_dword v146, v[164:165], off offset:64
	global_load_dwordx4 v[140:143], v[162:163], off offset:2048 nt
	global_load_dword v147, v[164:165], off offset:96
	s_waitcnt vmcnt(24)
	v_cmp_lt_i32_e64 s[8:9], 0, v56
	v_cmp_lt_i32_e64 s[22:23], 1, v56
	v_cmp_lt_i32_e64 s[24:25], 2, v56
	v_mov_b32_e32 v8, 0
	v_mov_b32_e32 v9, 0
	v_mov_b32_e32 v10, 0
	v_mov_b32_e32 v11, 0
	v_mov_b32_e32 v12, 0
	v_mov_b32_e32 v13, 0
	v_mov_b32_e32 v14, 0
	v_mov_b32_e32 v15, 0
	v_cndmask_b32_e64 v32, 0, v32, s[8:9]
	v_cndmask_b32_e64 v33, 0, v33, s[8:9]
	v_cndmask_b32_e64 v34, 0, v34, s[8:9]
	v_cndmask_b32_e64 v35, 0, v35, s[8:9]
	v_cndmask_b32_e64 v48, 0, v48, s[8:9]
	v_cndmask_b32_e64 v36, 0, v36, s[22:23]
	v_cndmask_b32_e64 v37, 0, v37, s[22:23]
	v_cndmask_b32_e64 v38, 0, v38, s[22:23]
	v_cndmask_b32_e64 v39, 0, v39, s[22:23]
	v_cndmask_b32_e64 v49, 0, v49, s[22:23]
	v_cndmask_b32_e64 v40, 0, v40, s[24:25]
	v_cndmask_b32_e64 v41, 0, v41, s[24:25]
	v_cndmask_b32_e64 v42, 0, v42, s[24:25]
	v_cndmask_b32_e64 v43, 0, v43, s[24:25]
	v_cndmask_b32_e64 v50, 0, v50, s[24:25]
	v_mov_b32_e32 v1, 0
	v_lshlrev_b32_e32 v166, 16, v32
	v_and_b32_e32 v167, 0xffff0000, v32
	v_lshlrev_b32_e32 v168, 16, v33
	v_and_b32_e32 v169, 0xffff0000, v33
	v_lshlrev_b32_e32 v170, 16, v34
	v_and_b32_e32 v171, 0xffff0000, v34
	v_lshlrev_b32_e32 v172, 16, v35
	v_and_b32_e32 v173, 0xffff0000, v35
	v_pk_add_f32 v[8:9], v[8:9], v[166:167]
	v_pk_add_f32 v[10:11], v[10:11], v[168:169]
	v_pk_add_f32 v[12:13], v[12:13], v[170:171]
	v_pk_add_f32 v[14:15], v[14:15], v[172:173]
	v_add_f32_e32 v1, v1, v48
	v_lshlrev_b32_e32 v166, 16, v36
	v_and_b32_e32 v167, 0xffff0000, v36
	v_lshlrev_b32_e32 v168, 16, v37
	v_and_b32_e32 v169, 0xffff0000, v37
	v_lshlrev_b32_e32 v170, 16, v38
	v_and_b32_e32 v171, 0xffff0000, v38
	v_lshlrev_b32_e32 v172, 16, v39
	v_and_b32_e32 v173, 0xffff0000, v39
	v_pk_add_f32 v[8:9], v[8:9], v[166:167]
	v_pk_add_f32 v[10:11], v[10:11], v[168:169]
	v_pk_add_f32 v[12:13], v[12:13], v[170:171]
	v_pk_add_f32 v[14:15], v[14:15], v[172:173]
	v_add_f32_e32 v1, v1, v49
	v_lshlrev_b32_e32 v166, 16, v40
	v_and_b32_e32 v167, 0xffff0000, v40
	v_lshlrev_b32_e32 v168, 16, v41
	v_and_b32_e32 v169, 0xffff0000, v41
	v_lshlrev_b32_e32 v170, 16, v42
	v_and_b32_e32 v171, 0xffff0000, v42
	v_lshlrev_b32_e32 v172, 16, v43
	v_and_b32_e32 v173, 0xffff0000, v43
	v_pk_add_f32 v[8:9], v[8:9], v[166:167]
	v_pk_add_f32 v[10:11], v[10:11], v[168:169]
	v_pk_add_f32 v[12:13], v[12:13], v[170:171]
	v_pk_add_f32 v[14:15], v[14:15], v[172:173]
	v_add_f32_e32 v1, v1, v50
	v_lshlrev_b32_e32 v166, 16, v44
	v_and_b32_e32 v167, 0xffff0000, v44
	v_lshlrev_b32_e32 v168, 16, v45
	v_and_b32_e32 v169, 0xffff0000, v45
	v_lshlrev_b32_e32 v170, 16, v46
	v_and_b32_e32 v171, 0xffff0000, v46
	v_lshlrev_b32_e32 v172, 16, v47
	v_and_b32_e32 v173, 0xffff0000, v47
	v_pk_add_f32 v[8:9], v[8:9], v[166:167]
	v_pk_add_f32 v[10:11], v[10:11], v[168:169]
	v_pk_add_f32 v[12:13], v[12:13], v[170:171]
	v_pk_add_f32 v[14:15], v[14:15], v[172:173]
	v_add_f32_e32 v1, v1, v51
	v_div_scale_f32 v21, s[8:9], v1, v1, 1.0
	v_rcp_f32_e32 v16, v21
	v_div_scale_f32 v28, vcc, 1.0, v1, 1.0
	v_fma_f32 v17, -v21, v16, 1.0
	v_fmac_f32_e32 v16, v17, v16
	v_mul_f32_e32 v17, v28, v16
	v_fma_f32 v22, -v21, v17, v28
	v_fmac_f32_e32 v17, v22, v16
	v_fma_f32 v21, -v21, v17, v28
	v_div_fmas_f32 v16, v21, v16, v17
	v_div_fixup_f32 v16, v16, v1, 1.0
	v_pk_mul_f32 v[8:9], v[16:17], v[8:9] op_sel_hi:[0,1]
	v_pk_mul_f32 v[10:11], v[16:17], v[10:11] op_sel_hi:[0,1]
	v_pk_mul_f32 v[12:13], v[16:17], v[12:13] op_sel_hi:[0,1]
	v_pk_mul_f32 v[14:15], v[16:17], v[14:15] op_sel_hi:[0,1]
	v_lshlrev_b64 v[160:161], 12, v[54:55]
	v_cvt_pk_bf16_f32 v24, v8, v9
	v_cvt_pk_bf16_f32 v25, v10, v11
	v_cvt_pk_bf16_f32 v26, v12, v13
	v_cvt_pk_bf16_f32 v27, v14, v15
	v_lshl_add_u64 v[160:161], v[6:7], 0, v[160:161]
	s_and_saveexec_b64 s[4:5], s[14:15]
	global_store_dwordx4 v[160:161], v[24:27], off sc1
	s_mov_b64 exec, s[4:5]
	s_waitcnt vmcnt(17)
	v_cmp_lt_i32_e64 s[8:9], 0, v88
	v_cmp_lt_i32_e64 s[22:23], 1, v88
	v_cmp_lt_i32_e64 s[24:25], 2, v88
	v_mov_b32_e32 v8, 0
	v_mov_b32_e32 v9, 0
	v_mov_b32_e32 v10, 0
	v_mov_b32_e32 v11, 0
	v_mov_b32_e32 v12, 0
	v_mov_b32_e32 v13, 0
	v_mov_b32_e32 v14, 0
	v_mov_b32_e32 v15, 0
	v_cndmask_b32_e64 v64, 0, v64, s[8:9]
	v_cndmask_b32_e64 v65, 0, v65, s[8:9]
	v_cndmask_b32_e64 v66, 0, v66, s[8:9]
	v_cndmask_b32_e64 v67, 0, v67, s[8:9]
	v_cndmask_b32_e64 v80, 0, v80, s[8:9]
	v_cndmask_b32_e64 v68, 0, v68, s[22:23]
	v_cndmask_b32_e64 v69, 0, v69, s[22:23]
	v_cndmask_b32_e64 v70, 0, v70, s[22:23]
	v_cndmask_b32_e64 v71, 0, v71, s[22:23]
	v_cndmask_b32_e64 v81, 0, v81, s[22:23]
	v_cndmask_b32_e64 v72, 0, v72, s[24:25]
	v_cndmask_b32_e64 v73, 0, v73, s[24:25]
	v_cndmask_b32_e64 v74, 0, v74, s[24:25]
	v_cndmask_b32_e64 v75, 0, v75, s[24:25]
	v_cndmask_b32_e64 v82, 0, v82, s[24:25]
	v_mov_b32_e32 v1, 0
	v_lshlrev_b32_e32 v166, 16, v64
	v_and_b32_e32 v167, 0xffff0000, v64
	v_lshlrev_b32_e32 v168, 16, v65
	v_and_b32_e32 v169, 0xffff0000, v65
	v_lshlrev_b32_e32 v170, 16, v66
	v_and_b32_e32 v171, 0xffff0000, v66
	v_lshlrev_b32_e32 v172, 16, v67
	v_and_b32_e32 v173, 0xffff0000, v67
	v_pk_add_f32 v[8:9], v[8:9], v[166:167]
	v_pk_add_f32 v[10:11], v[10:11], v[168:169]
	v_pk_add_f32 v[12:13], v[12:13], v[170:171]
	v_pk_add_f32 v[14:15], v[14:15], v[172:173]
	v_add_f32_e32 v1, v1, v80
	v_lshlrev_b32_e32 v166, 16, v68
	v_and_b32_e32 v167, 0xffff0000, v68
	v_lshlrev_b32_e32 v168, 16, v69
	v_and_b32_e32 v169, 0xffff0000, v69
	v_lshlrev_b32_e32 v170, 16, v70
	v_and_b32_e32 v171, 0xffff0000, v70
	v_lshlrev_b32_e32 v172, 16, v71
	v_and_b32_e32 v173, 0xffff0000, v71
	v_pk_add_f32 v[8:9], v[8:9], v[166:167]
	v_pk_add_f32 v[10:11], v[10:11], v[168:169]
	v_pk_add_f32 v[12:13], v[12:13], v[170:171]
	v_pk_add_f32 v[14:15], v[14:15], v[172:173]
	v_add_f32_e32 v1, v1, v81
	v_lshlrev_b32_e32 v166, 16, v72
	v_and_b32_e32 v167, 0xffff0000, v72
	v_lshlrev_b32_e32 v168, 16, v73
	v_and_b32_e32 v169, 0xffff0000, v73
	v_lshlrev_b32_e32 v170, 16, v74
	v_and_b32_e32 v171, 0xffff0000, v74
	v_lshlrev_b32_e32 v172, 16, v75
	v_and_b32_e32 v173, 0xffff0000, v75
	v_pk_add_f32 v[8:9], v[8:9], v[166:167]
	v_pk_add_f32 v[10:11], v[10:11], v[168:169]
	v_pk_add_f32 v[12:13], v[12:13], v[170:171]
	v_pk_add_f32 v[14:15], v[14:15], v[172:173]
	v_add_f32_e32 v1, v1, v82
	v_lshlrev_b32_e32 v166, 16, v76
	v_and_b32_e32 v167, 0xffff0000, v76
	v_lshlrev_b32_e32 v168, 16, v77
	v_and_b32_e32 v169, 0xffff0000, v77
	v_lshlrev_b32_e32 v170, 16, v78
	v_and_b32_e32 v171, 0xffff0000, v78
	v_lshlrev_b32_e32 v172, 16, v79
	v_and_b32_e32 v173, 0xffff0000, v79
	v_pk_add_f32 v[8:9], v[8:9], v[166:167]
	v_pk_add_f32 v[10:11], v[10:11], v[168:169]
	v_pk_add_f32 v[12:13], v[12:13], v[170:171]
	v_pk_add_f32 v[14:15], v[14:15], v[172:173]
	v_add_f32_e32 v1, v1, v83
	v_div_scale_f32 v21, s[8:9], v1, v1, 1.0
	v_rcp_f32_e32 v16, v21
	v_div_scale_f32 v28, vcc, 1.0, v1, 1.0
	v_fma_f32 v17, -v21, v16, 1.0
	v_fmac_f32_e32 v16, v17, v16
	v_mul_f32_e32 v17, v28, v16
	v_fma_f32 v22, -v21, v17, v28
	v_fmac_f32_e32 v17, v22, v16
	v_fma_f32 v21, -v21, v17, v28
	v_div_fmas_f32 v16, v21, v16, v17
	v_div_fixup_f32 v16, v16, v1, 1.0
	v_pk_mul_f32 v[8:9], v[16:17], v[8:9] op_sel_hi:[0,1]
	v_pk_mul_f32 v[10:11], v[16:17], v[10:11] op_sel_hi:[0,1]
	v_pk_mul_f32 v[12:13], v[16:17], v[12:13] op_sel_hi:[0,1]
	v_pk_mul_f32 v[14:15], v[16:17], v[14:15] op_sel_hi:[0,1]
	v_lshlrev_b64 v[160:161], 12, v[86:87]
	v_cvt_pk_bf16_f32 v24, v8, v9
	v_cvt_pk_bf16_f32 v25, v10, v11
	v_cvt_pk_bf16_f32 v26, v12, v13
	v_cvt_pk_bf16_f32 v27, v14, v15
	v_lshl_add_u64 v[160:161], v[6:7], 0, v[160:161]
	s_and_saveexec_b64 s[4:5], s[16:17]
	global_store_dwordx4 v[160:161], v[24:27], off sc1
	s_mov_b64 exec, s[4:5]
	s_waitcnt vmcnt(10)
	v_cmp_lt_i32_e64 s[8:9], 0, v120
	v_cmp_lt_i32_e64 s[22:23], 1, v120
	v_cmp_lt_i32_e64 s[24:25], 2, v120
	v_mov_b32_e32 v8, 0
	v_mov_b32_e32 v9, 0
	v_mov_b32_e32 v10, 0
	v_mov_b32_e32 v11, 0
	v_mov_b32_e32 v12, 0
	v_mov_b32_e32 v13, 0
	v_mov_b32_e32 v14, 0
	v_mov_b32_e32 v15, 0
	v_cndmask_b32_e64 v96, 0, v96, s[8:9]
	v_cndmask_b32_e64 v97, 0, v97, s[8:9]
	v_cndmask_b32_e64 v98, 0, v98, s[8:9]
	v_cndmask_b32_e64 v99, 0, v99, s[8:9]
	v_cndmask_b32_e64 v112, 0, v112, s[8:9]
	v_cndmask_b32_e64 v100, 0, v100, s[22:23]
	v_cndmask_b32_e64 v101, 0, v101, s[22:23]
	v_cndmask_b32_e64 v102, 0, v102, s[22:23]
	v_cndmask_b32_e64 v103, 0, v103, s[22:23]
	v_cndmask_b32_e64 v113, 0, v113, s[22:23]
	v_cndmask_b32_e64 v104, 0, v104, s[24:25]
	v_cndmask_b32_e64 v105, 0, v105, s[24:25]
	v_cndmask_b32_e64 v106, 0, v106, s[24:25]
	v_cndmask_b32_e64 v107, 0, v107, s[24:25]
	v_cndmask_b32_e64 v114, 0, v114, s[24:25]
	v_mov_b32_e32 v1, 0
	v_lshlrev_b32_e32 v166, 16, v96
	v_and_b32_e32 v167, 0xffff0000, v96
	v_lshlrev_b32_e32 v168, 16, v97
	v_and_b32_e32 v169, 0xffff0000, v97
	v_lshlrev_b32_e32 v170, 16, v98
	v_and_b32_e32 v171, 0xffff0000, v98
	v_lshlrev_b32_e32 v172, 16, v99
	v_and_b32_e32 v173, 0xffff0000, v99
	v_pk_add_f32 v[8:9], v[8:9], v[166:167]
	v_pk_add_f32 v[10:11], v[10:11], v[168:169]
	v_pk_add_f32 v[12:13], v[12:13], v[170:171]
	v_pk_add_f32 v[14:15], v[14:15], v[172:173]
	v_add_f32_e32 v1, v1, v112
	v_lshlrev_b32_e32 v166, 16, v100
	v_and_b32_e32 v167, 0xffff0000, v100
	v_lshlrev_b32_e32 v168, 16, v101
	v_and_b32_e32 v169, 0xffff0000, v101
	v_lshlrev_b32_e32 v170, 16, v102
	v_and_b32_e32 v171, 0xffff0000, v102
	v_lshlrev_b32_e32 v172, 16, v103
	v_and_b32_e32 v173, 0xffff0000, v103
	v_pk_add_f32 v[8:9], v[8:9], v[166:167]
	v_pk_add_f32 v[10:11], v[10:11], v[168:169]
	v_pk_add_f32 v[12:13], v[12:13], v[170:171]
	v_pk_add_f32 v[14:15], v[14:15], v[172:173]
	v_add_f32_e32 v1, v1, v113
	v_lshlrev_b32_e32 v166, 16, v104
	v_and_b32_e32 v167, 0xffff0000, v104
	v_lshlrev_b32_e32 v168, 16, v105
	v_and_b32_e32 v169, 0xffff0000, v105
	v_lshlrev_b32_e32 v170, 16, v106
	v_and_b32_e32 v171, 0xffff0000, v106
	v_lshlrev_b32_e32 v172, 16, v107
	v_and_b32_e32 v173, 0xffff0000, v107
	v_pk_add_f32 v[8:9], v[8:9], v[166:167]
	v_pk_add_f32 v[10:11], v[10:11], v[168:169]
	v_pk_add_f32 v[12:13], v[12:13], v[170:171]
	v_pk_add_f32 v[14:15], v[14:15], v[172:173]
	v_add_f32_e32 v1, v1, v114
	v_lshlrev_b32_e32 v166, 16, v108
	v_and_b32_e32 v167, 0xffff0000, v108
	v_lshlrev_b32_e32 v168, 16, v109
	v_and_b32_e32 v169, 0xffff0000, v109
	v_lshlrev_b32_e32 v170, 16, v110
	v_and_b32_e32 v171, 0xffff0000, v110
	v_lshlrev_b32_e32 v172, 16, v111
	v_and_b32_e32 v173, 0xffff0000, v111
	v_pk_add_f32 v[8:9], v[8:9], v[166:167]
	v_pk_add_f32 v[10:11], v[10:11], v[168:169]
	v_pk_add_f32 v[12:13], v[12:13], v[170:171]
	v_pk_add_f32 v[14:15], v[14:15], v[172:173]
	v_add_f32_e32 v1, v1, v115
	v_div_scale_f32 v21, s[8:9], v1, v1, 1.0
	v_rcp_f32_e32 v16, v21
	v_div_scale_f32 v28, vcc, 1.0, v1, 1.0
	v_fma_f32 v17, -v21, v16, 1.0
	v_fmac_f32_e32 v16, v17, v16
	v_mul_f32_e32 v17, v28, v16
	v_fma_f32 v22, -v21, v17, v28
	v_fmac_f32_e32 v17, v22, v16
	v_fma_f32 v21, -v21, v17, v28
	v_div_fmas_f32 v16, v21, v16, v17
	v_div_fixup_f32 v16, v16, v1, 1.0
	v_pk_mul_f32 v[8:9], v[16:17], v[8:9] op_sel_hi:[0,1]
	v_pk_mul_f32 v[10:11], v[16:17], v[10:11] op_sel_hi:[0,1]
	v_pk_mul_f32 v[12:13], v[16:17], v[12:13] op_sel_hi:[0,1]
	v_pk_mul_f32 v[14:15], v[16:17], v[14:15] op_sel_hi:[0,1]
	v_lshlrev_b64 v[160:161], 12, v[118:119]
	v_cvt_pk_bf16_f32 v24, v8, v9
	v_cvt_pk_bf16_f32 v25, v10, v11
	v_cvt_pk_bf16_f32 v26, v12, v13
	v_cvt_pk_bf16_f32 v27, v14, v15
	v_lshl_add_u64 v[160:161], v[6:7], 0, v[160:161]
	s_and_saveexec_b64 s[4:5], s[18:19]
	global_store_dwordx4 v[160:161], v[24:27], off sc1
	s_mov_b64 exec, s[4:5]
	s_waitcnt vmcnt(3)
	v_cmp_lt_i32_e64 s[8:9], 0, v152
	v_cmp_lt_i32_e64 s[22:23], 1, v152
	v_cmp_lt_i32_e64 s[24:25], 2, v152
	v_mov_b32_e32 v8, 0
	v_mov_b32_e32 v9, 0
	v_mov_b32_e32 v10, 0
	v_mov_b32_e32 v11, 0
	v_mov_b32_e32 v12, 0
	v_mov_b32_e32 v13, 0
	v_mov_b32_e32 v14, 0
	v_mov_b32_e32 v15, 0
	v_cndmask_b32_e64 v128, 0, v128, s[8:9]
	v_cndmask_b32_e64 v129, 0, v129, s[8:9]
	v_cndmask_b32_e64 v130, 0, v130, s[8:9]
	v_cndmask_b32_e64 v131, 0, v131, s[8:9]
	v_cndmask_b32_e64 v144, 0, v144, s[8:9]
	v_cndmask_b32_e64 v132, 0, v132, s[22:23]
	v_cndmask_b32_e64 v133, 0, v133, s[22:23]
	v_cndmask_b32_e64 v134, 0, v134, s[22:23]
	v_cndmask_b32_e64 v135, 0, v135, s[22:23]
	v_cndmask_b32_e64 v145, 0, v145, s[22:23]
	v_cndmask_b32_e64 v136, 0, v136, s[24:25]
	v_cndmask_b32_e64 v137, 0, v137, s[24:25]
	v_cndmask_b32_e64 v138, 0, v138, s[24:25]
	v_cndmask_b32_e64 v139, 0, v139, s[24:25]
	v_cndmask_b32_e64 v146, 0, v146, s[24:25]
	v_mov_b32_e32 v1, 0
	v_lshlrev_b32_e32 v166, 16, v128
	v_and_b32_e32 v167, 0xffff0000, v128
	v_lshlrev_b32_e32 v168, 16, v129
	v_and_b32_e32 v169, 0xffff0000, v129
	v_lshlrev_b32_e32 v170, 16, v130
	v_and_b32_e32 v171, 0xffff0000, v130
	v_lshlrev_b32_e32 v172, 16, v131
	v_and_b32_e32 v173, 0xffff0000, v131
	v_pk_add_f32 v[8:9], v[8:9], v[166:167]
	v_pk_add_f32 v[10:11], v[10:11], v[168:169]
	v_pk_add_f32 v[12:13], v[12:13], v[170:171]
	v_pk_add_f32 v[14:15], v[14:15], v[172:173]
	v_add_f32_e32 v1, v1, v144
	v_lshlrev_b32_e32 v166, 16, v132
	v_and_b32_e32 v167, 0xffff0000, v132
	v_lshlrev_b32_e32 v168, 16, v133
	v_and_b32_e32 v169, 0xffff0000, v133
	v_lshlrev_b32_e32 v170, 16, v134
	v_and_b32_e32 v171, 0xffff0000, v134
	v_lshlrev_b32_e32 v172, 16, v135
	v_and_b32_e32 v173, 0xffff0000, v135
	v_pk_add_f32 v[8:9], v[8:9], v[166:167]
	v_pk_add_f32 v[10:11], v[10:11], v[168:169]
	v_pk_add_f32 v[12:13], v[12:13], v[170:171]
	v_pk_add_f32 v[14:15], v[14:15], v[172:173]
	v_add_f32_e32 v1, v1, v145
	v_lshlrev_b32_e32 v166, 16, v136
	v_and_b32_e32 v167, 0xffff0000, v136
	v_lshlrev_b32_e32 v168, 16, v137
	v_and_b32_e32 v169, 0xffff0000, v137
	v_lshlrev_b32_e32 v170, 16, v138
	v_and_b32_e32 v171, 0xffff0000, v138
	v_lshlrev_b32_e32 v172, 16, v139
	v_and_b32_e32 v173, 0xffff0000, v139
	v_pk_add_f32 v[8:9], v[8:9], v[166:167]
	v_pk_add_f32 v[10:11], v[10:11], v[168:169]
	v_pk_add_f32 v[12:13], v[12:13], v[170:171]
	v_pk_add_f32 v[14:15], v[14:15], v[172:173]
	v_add_f32_e32 v1, v1, v146
	v_lshlrev_b32_e32 v166, 16, v140
	v_and_b32_e32 v167, 0xffff0000, v140
	v_lshlrev_b32_e32 v168, 16, v141
	v_and_b32_e32 v169, 0xffff0000, v141
	v_lshlrev_b32_e32 v170, 16, v142
	v_and_b32_e32 v171, 0xffff0000, v142
	v_lshlrev_b32_e32 v172, 16, v143
	v_and_b32_e32 v173, 0xffff0000, v143
	v_pk_add_f32 v[8:9], v[8:9], v[166:167]
	v_pk_add_f32 v[10:11], v[10:11], v[168:169]
	v_pk_add_f32 v[12:13], v[12:13], v[170:171]
	v_pk_add_f32 v[14:15], v[14:15], v[172:173]
	v_add_f32_e32 v1, v1, v147
	v_div_scale_f32 v21, s[8:9], v1, v1, 1.0
	v_rcp_f32_e32 v16, v21
	v_div_scale_f32 v28, vcc, 1.0, v1, 1.0
	v_fma_f32 v17, -v21, v16, 1.0
	v_fmac_f32_e32 v16, v17, v16
	v_mul_f32_e32 v17, v28, v16
	v_fma_f32 v22, -v21, v17, v28
	v_fmac_f32_e32 v17, v22, v16
	v_fma_f32 v21, -v21, v17, v28
	v_div_fmas_f32 v16, v21, v16, v17
	v_div_fixup_f32 v16, v16, v1, 1.0
	v_pk_mul_f32 v[8:9], v[16:17], v[8:9] op_sel_hi:[0,1]
	v_pk_mul_f32 v[10:11], v[16:17], v[10:11] op_sel_hi:[0,1]
	v_pk_mul_f32 v[12:13], v[16:17], v[12:13] op_sel_hi:[0,1]
	v_pk_mul_f32 v[14:15], v[16:17], v[14:15] op_sel_hi:[0,1]
	v_lshlrev_b64 v[160:161], 12, v[150:151]
	v_cvt_pk_bf16_f32 v24, v8, v9
	v_cvt_pk_bf16_f32 v25, v10, v11
	v_cvt_pk_bf16_f32 v26, v12, v13
	v_cvt_pk_bf16_f32 v27, v14, v15
	v_lshl_add_u64 v[160:161], v[6:7], 0, v[160:161]
	s_and_saveexec_b64 s[4:5], s[20:21]
	global_store_dwordx4 v[160:161], v[24:27], off sc1
	s_mov_b64 exec, s[4:5]
	s_lshl_b32 s12, s11, 2
	v_add_u32_e32 v20, s12, v20
	v_cmp_le_i32_e32 vcc, s10, v20
	s_or_b64 s[2:3], vcc, s[2:3]
	s_andn2_b64 exec, exec, s[2:3]
	s_cbranch_execnz .Lc4_outer
